# v39 + residual GEMM epilogue (bf16 path): next row group's first read-modify-write load issued after the current group's last v_pk_add, waited with vmcnt(2) instead of load + vmcnt(0)
# baseline (speedup 1.0000x reference)
; __device__ __forceinline__ u32x4 pack8(const f32x4 a, const f32x4 b) { u32x4 w; w.x = cvt_pk_bf16(a[0], a[1]); w.y = cvt_pk_bf16(a[2], a[3]); w.z = cvt_pk_bf16(b[0], b[1]); w.w = cvt_pk_bf16(b[2], b[3]); return w; }
;     __device__ __forceinline__ void operator()(const f32x4 (&acc)[2][2][4][2], const Unit& u, int wr, int wc, int fr, int fq) const {
;     ...
;             for (int m = 0; m < 4; ++m) { const int row = row0 + ai * HALF + m * 16; bf16_t* hp = Hx + (size_t)row * 1024;
;                 if (from_f32) { const float* xin = row < 16384 ? xa + (size_t)row * 1024 : xb + (size_t)(row - 16384) * 1024;
; #pragma unroll
;                     for (int bj = 0; bj < 2; ++bj) { const int c = col0 + bj * HALF; const f32x4 r0 = *(const f32x4*)(xin + c), r1 = *(const f32x4*)(xin + c + 4);
;                         *(u32x4*)(hp + c) = pack8(r0 + acc[ai][bj][m][0], r1 + acc[ai][bj][m][1]); }
;                 } else {
; #pragma unroll
;                     for (int bj = 0; bj < 2; ++bj) { const int c = col0 + bj * HALF; const u32x4 w = *(const u32x4*)(hp + c); f32x4 r0, r1;
;                         r0[0] = __uint_as_float(w.x << 16); r0[1] = __uint_as_float(w.x & 0xffff0000u); r0[2] = __uint_as_float(w.y << 16); r0[3] = __uint_as_float(w.y & 0xffff0000u);
;                         r1[0] = __uint_as_float(w.z << 16); r1[1] = __uint_as_float(w.z & 0xffff0000u); r1[2] = __uint_as_float(w.w << 16); r1[3] = __uint_as_float(w.w & 0xffff0000u);
;                         *(u32x4*)(hp + c) = pack8(r0 + acc[ai][bj][m][0], r1 + acc[ai][bj][m][1]); }
.LBB0_85:
	v_lshl_add_u32 v144, s13, 8, v148
	v_readlane_b32 s100, v252, 23
	v_readlane_b32 s101, v252, 24
	s_lshr_b32 vcc_lo, s33, 6
	s_and_b32 vcc_lo, vcc_lo, 3
	s_lshl_b32 vcc_lo, vcc_lo, 2
	s_lshl_b32 vcc_hi, s0, 4
	s_add_i32 vcc_lo, vcc_lo, vcc_hi
	s_mul_i32 vcc_lo, vcc_lo, 0x50000
	s_add_u32 s100, s100, vcc_lo
	s_addc_u32 s101, s101, 0
	s_add_u32 s100, s100, 0x36600000
	s_addc_u32 s101, s101, 0
	v_mbcnt_lo_u32_b32 v254, -1, 0
	v_mbcnt_hi_u32_b32 v254, -1, v254
	v_lshrrev_b32_e32 v254, 4, v254
	v_mul_u32_u24_e32 v254, 0x50000, v254
	v_lshl_add_u32 v255, v144, 2, v254
	v_ashrrev_i32_e32 v145, 31, v144
	v_lshl_or_b32 v142, s0, 8, v150
	v_lshlrev_b64 v[146:147], 11, v[144:145]
	v_cndmask_b32_e64 v0, 0, 1, s[80:81]
	v_lshl_add_u64 v[146:147], s[60:61], 0, v[146:147]
	s_mov_b64 s[4:5], -1
	v_cmp_ne_u32_e64 s[8:9], 1, v0
	s_andn2_b64 vcc, exec, s[80:81]
	v_ashrrev_i32_e32 v143, 31, v142
	s_cbranch_vccnz .LBB0_87
	v_lshl_add_u64 v[160:161], v[142:143], 1, v[146:147]
	global_load_dwordx4 v[152:155], v[160:161], off
	s_mov_b64 s[4:5], 0
	s_waitcnt vmcnt(0)
	v_lshlrev_b32_e32 v156, 16, v152
	v_and_b32_e32 v157, 0xffff0000, v152
	v_lshlrev_b32_e32 v152, 16, v153
	v_and_b32_e32 v153, 0xffff0000, v153
	v_lshlrev_b32_e32 v158, 16, v154
	v_and_b32_e32 v159, 0xffff0000, v154
	v_lshlrev_b32_e32 v154, 16, v155
	v_and_b32_e32 v155, 0xffff0000, v155
	v_pk_add_f32 v[162:163], v[128:129], v[152:153]
	v_pk_add_f32 v[152:153], v[126:127], v[156:157]
	v_pk_add_f32 v[156:157], v[124:125], v[154:155]
	v_pk_add_f32 v[154:155], v[122:123], v[158:159]
	v_cvt_pk_bf16_f32 v152, v152, v153
	v_cvt_pk_bf16_f32 v153, v162, v163
	s_nop 0
	v_cvt_pk_bf16_f32 v154, v154, v155
	v_cvt_pk_bf16_f32 v155, v156, v157
	global_load_dwordx4 v[156:159], v[160:161], off offset:256
	s_nop 0
	v_lshlrev_b32_e32 v254, 16, v152
	v_mul_f32_e32 v253, v254, v254
	v_and_b32_e32 v254, 0xffff0000, v152
	v_fmac_f32_e32 v253, v254, v254
	v_lshlrev_b32_e32 v254, 16, v153
	v_fmac_f32_e32 v253, v254, v254
	v_and_b32_e32 v254, 0xffff0000, v153
	v_fmac_f32_e32 v253, v254, v254
	v_lshlrev_b32_e32 v254, 16, v154
	v_fmac_f32_e32 v253, v254, v254
	v_and_b32_e32 v254, 0xffff0000, v154
	v_fmac_f32_e32 v253, v254, v254
	v_lshlrev_b32_e32 v254, 16, v155
	v_fmac_f32_e32 v253, v254, v254
	v_and_b32_e32 v254, 0xffff0000, v155
	v_fmac_f32_e32 v253, v254, v254
	global_store_dwordx4 v[160:161], v[152:155], off
	s_waitcnt vmcnt(1)
	s_nop 0
	v_lshlrev_b32_e32 v152, 16, v156
	v_and_b32_e32 v153, 0xffff0000, v156
	v_lshlrev_b32_e32 v154, 16, v157
	v_and_b32_e32 v155, 0xffff0000, v157
	v_lshlrev_b32_e32 v156, 16, v158
	v_and_b32_e32 v157, 0xffff0000, v158
	v_lshlrev_b32_e32 v158, 16, v159
	v_and_b32_e32 v159, 0xffff0000, v159
	v_pk_add_f32 v[154:155], v[120:121], v[154:155]
	v_pk_add_f32 v[152:153], v[118:119], v[152:153]
	v_pk_add_f32 v[158:159], v[116:117], v[158:159]
	v_pk_add_f32 v[156:157], v[114:115], v[156:157]
	v_or_b32_e32 v116, 16, v144
	v_ashrrev_i32_e32 v117, 31, v116
	v_lshlrev_b64 v[114:115], 11, v[116:117]
	v_lshl_add_u64 v[114:115], s[60:61], 0, v[114:115]
	v_lshl_add_u64 v[126:127], v[142:143], 1, v[114:115]
	global_load_dwordx4 v[118:121], v[126:127], off
	v_cvt_pk_bf16_f32 v152, v152, v153
	v_cvt_pk_bf16_f32 v153, v154, v155
	s_nop 0
	v_cvt_pk_bf16_f32 v154, v156, v157
	v_cvt_pk_bf16_f32 v155, v158, v159
	v_lshlrev_b32_e32 v254, 16, v152
	v_fmac_f32_e32 v253, v254, v254
	v_and_b32_e32 v254, 0xffff0000, v152
	v_fmac_f32_e32 v253, v254, v254
	v_lshlrev_b32_e32 v254, 16, v153
	v_fmac_f32_e32 v253, v254, v254
	v_and_b32_e32 v254, 0xffff0000, v153
	v_fmac_f32_e32 v253, v254, v254
	v_lshlrev_b32_e32 v254, 16, v154
	v_fmac_f32_e32 v253, v254, v254
	v_and_b32_e32 v254, 0xffff0000, v154
	v_fmac_f32_e32 v253, v254, v254
	v_lshlrev_b32_e32 v254, 16, v155
	v_fmac_f32_e32 v253, v254, v254
	v_and_b32_e32 v254, 0xffff0000, v155
	v_fmac_f32_e32 v253, v254, v254
	global_store_dwordx4 v[160:161], v[152:155], off offset:256
	global_store_dword v255, v253, s[100:101]

; __device__ __forceinline__ u32x4 pack8(const f32x4 a, const f32x4 b) { u32x4 w; w.x = cvt_pk_bf16(a[0], a[1]); w.y = cvt_pk_bf16(a[2], a[3]); w.z = cvt_pk_bf16(b[0], b[1]); w.w = cvt_pk_bf16(b[2], b[3]); return w; }
;     __device__ __forceinline__ void operator()(const f32x4 (&acc)[2][2][4][2], const Unit& u, int wr, int wc, int fr, int fq) const {
;     ...
;             for (int m = 0; m < 4; ++m) { const int row = row0 + ai * HALF + m * 16; bf16_t* hp = Hx + (size_t)row * 1024;
;                 if (from_f32) { const float* xin = row < 16384 ? xa + (size_t)row * 1024 : xb + (size_t)(row - 16384) * 1024;
; #pragma unroll
;                     for (int bj = 0; bj < 2; ++bj) { const int c = col0 + bj * HALF; const f32x4 r0 = *(const f32x4*)(xin + c), r1 = *(const f32x4*)(xin + c + 4);
;                         *(u32x4*)(hp + c) = pack8(r0 + acc[ai][bj][m][0], r1 + acc[ai][bj][m][1]); }
;                 } else {
; #pragma unroll
;                     for (int bj = 0; bj < 2; ++bj) { const int c = col0 + bj * HALF; const u32x4 w = *(const u32x4*)(hp + c); f32x4 r0, r1;
;                         r0[0] = __uint_as_float(w.x << 16); r0[1] = __uint_as_float(w.x & 0xffff0000u); r0[2] = __uint_as_float(w.y << 16); r0[3] = __uint_as_float(w.y & 0xffff0000u);
;                         r1[0] = __uint_as_float(w.z << 16); r1[1] = __uint_as_float(w.z & 0xffff0000u); r1[2] = __uint_as_float(w.w << 16); r1[3] = __uint_as_float(w.w & 0xffff0000u);
;                         *(u32x4*)(hp + c) = pack8(r0 + acc[ai][bj][m][0], r1 + acc[ai][bj][m][1]); }
.LBB0_89:
	s_nop 1
	v_or_b32_e32 v116, 16, v144
	v_ashrrev_i32_e32 v117, 31, v116
	v_lshlrev_b64 v[114:115], 11, v[116:117]
	v_lshl_add_u64 v[114:115], s[60:61], 0, v[114:115]
	s_and_b64 vcc, exec, s[8:9]
	s_mov_b64 s[4:5], -1
	s_cbranch_vccnz .LBB0_91
	v_lshl_add_u64 v[126:127], v[142:143], 1, v[114:115]
	s_mov_b64 s[4:5], 0
	s_waitcnt vmcnt(2)
	v_lshlrev_b32_e32 v122, 16, v118
	v_and_b32_e32 v123, 0xffff0000, v118
	v_lshlrev_b32_e32 v118, 16, v119
	v_and_b32_e32 v119, 0xffff0000, v119
	v_lshlrev_b32_e32 v124, 16, v120
	v_and_b32_e32 v125, 0xffff0000, v120
	v_lshlrev_b32_e32 v120, 16, v121
	v_and_b32_e32 v121, 0xffff0000, v121
	v_pk_add_f32 v[128:129], v[112:113], v[118:119]
	v_pk_add_f32 v[118:119], v[110:111], v[122:123]
	v_pk_add_f32 v[122:123], v[108:109], v[120:121]
	v_pk_add_f32 v[120:121], v[106:107], v[124:125]
	v_cvt_pk_bf16_f32 v118, v118, v119
	v_cvt_pk_bf16_f32 v119, v128, v129
	s_nop 0
	v_cvt_pk_bf16_f32 v120, v120, v121
	v_cvt_pk_bf16_f32 v121, v122, v123
	global_load_dwordx4 v[122:125], v[126:127], off offset:256
	s_nop 0
	v_lshlrev_b32_e32 v254, 16, v118
	v_mul_f32_e32 v253, v254, v254
	v_and_b32_e32 v254, 0xffff0000, v118
	v_fmac_f32_e32 v253, v254, v254
	v_lshlrev_b32_e32 v254, 16, v119
	v_fmac_f32_e32 v253, v254, v254
	v_and_b32_e32 v254, 0xffff0000, v119
	v_fmac_f32_e32 v253, v254, v254
	v_lshlrev_b32_e32 v254, 16, v120
	v_fmac_f32_e32 v253, v254, v254
	v_and_b32_e32 v254, 0xffff0000, v120
	v_fmac_f32_e32 v253, v254, v254
	v_lshlrev_b32_e32 v254, 16, v121
	v_fmac_f32_e32 v253, v254, v254
	v_and_b32_e32 v254, 0xffff0000, v121
	v_fmac_f32_e32 v253, v254, v254
	global_store_dwordx4 v[126:127], v[118:121], off
	s_waitcnt vmcnt(1)
	s_nop 0
	v_lshlrev_b32_e32 v118, 16, v122
	v_and_b32_e32 v119, 0xffff0000, v122
	v_lshlrev_b32_e32 v120, 16, v123
	v_and_b32_e32 v121, 0xffff0000, v123
	v_lshlrev_b32_e32 v122, 16, v124
	v_and_b32_e32 v123, 0xffff0000, v124
	v_lshlrev_b32_e32 v124, 16, v125
	v_and_b32_e32 v125, 0xffff0000, v125
	v_pk_add_f32 v[120:121], v[104:105], v[120:121]
	v_pk_add_f32 v[118:119], v[102:103], v[118:119]
	v_pk_add_f32 v[124:125], v[100:101], v[124:125]
	v_pk_add_f32 v[122:123], v[98:99], v[122:123]
	v_or_b32_e32 v100, 32, v144
	v_ashrrev_i32_e32 v101, 31, v100
	v_lshlrev_b64 v[98:99], 11, v[100:101]
	v_lshl_add_u64 v[98:99], s[60:61], 0, v[98:99]
	v_lshl_add_u64 v[110:111], v[142:143], 1, v[98:99]
	global_load_dwordx4 v[102:105], v[110:111], off
	v_cvt_pk_bf16_f32 v118, v118, v119
	v_cvt_pk_bf16_f32 v119, v120, v121
	s_nop 0
	v_cvt_pk_bf16_f32 v120, v122, v123
	v_cvt_pk_bf16_f32 v121, v124, v125
	v_lshlrev_b32_e32 v254, 16, v118
	v_fmac_f32_e32 v253, v254, v254
	v_and_b32_e32 v254, 0xffff0000, v118
	v_fmac_f32_e32 v253, v254, v254
	v_lshlrev_b32_e32 v254, 16, v119
	v_fmac_f32_e32 v253, v254, v254
	v_and_b32_e32 v254, 0xffff0000, v119
	v_fmac_f32_e32 v253, v254, v254
	v_lshlrev_b32_e32 v254, 16, v120
	v_fmac_f32_e32 v253, v254, v254
	v_and_b32_e32 v254, 0xffff0000, v120
	v_fmac_f32_e32 v253, v254, v254
	v_lshlrev_b32_e32 v254, 16, v121
	v_fmac_f32_e32 v253, v254, v254
	v_and_b32_e32 v254, 0xffff0000, v121
	v_fmac_f32_e32 v253, v254, v254
	global_store_dwordx4 v[126:127], v[118:121], off offset:256
	global_store_dword v255, v253, s[100:101] offset:64

; __device__ __forceinline__ u32x4 pack8(const f32x4 a, const f32x4 b) { u32x4 w; w.x = cvt_pk_bf16(a[0], a[1]); w.y = cvt_pk_bf16(a[2], a[3]); w.z = cvt_pk_bf16(b[0], b[1]); w.w = cvt_pk_bf16(b[2], b[3]); return w; }
;     __device__ __forceinline__ void operator()(const f32x4 (&acc)[2][2][4][2], const Unit& u, int wr, int wc, int fr, int fq) const {
;     ...
;             for (int m = 0; m < 4; ++m) { const int row = row0 + ai * HALF + m * 16; bf16_t* hp = Hx + (size_t)row * 1024;
;                 if (from_f32) { const float* xin = row < 16384 ? xa + (size_t)row * 1024 : xb + (size_t)(row - 16384) * 1024;
; #pragma unroll
;                     for (int bj = 0; bj < 2; ++bj) { const int c = col0 + bj * HALF; const f32x4 r0 = *(const f32x4*)(xin + c), r1 = *(const f32x4*)(xin + c + 4);
;                         *(u32x4*)(hp + c) = pack8(r0 + acc[ai][bj][m][0], r1 + acc[ai][bj][m][1]); }
;                 } else {
; #pragma unroll
;                     for (int bj = 0; bj < 2; ++bj) { const int c = col0 + bj * HALF; const u32x4 w = *(const u32x4*)(hp + c); f32x4 r0, r1;
;                         r0[0] = __uint_as_float(w.x << 16); r0[1] = __uint_as_float(w.x & 0xffff0000u); r0[2] = __uint_as_float(w.y << 16); r0[3] = __uint_as_float(w.y & 0xffff0000u);
;                         r1[0] = __uint_as_float(w.z << 16); r1[1] = __uint_as_float(w.z & 0xffff0000u); r1[2] = __uint_as_float(w.w << 16); r1[3] = __uint_as_float(w.w & 0xffff0000u);
;                         *(u32x4*)(hp + c) = pack8(r0 + acc[ai][bj][m][0], r1 + acc[ai][bj][m][1]); }
.LBB0_93:
	s_nop 1
	v_or_b32_e32 v100, 32, v144
	v_ashrrev_i32_e32 v101, 31, v100
	v_lshlrev_b64 v[98:99], 11, v[100:101]
	v_lshl_add_u64 v[98:99], s[60:61], 0, v[98:99]
	s_and_b64 vcc, exec, s[8:9]
	s_mov_b64 s[4:5], -1
	s_cbranch_vccnz .LBB0_95
	v_lshl_add_u64 v[110:111], v[142:143], 1, v[98:99]
	s_mov_b64 s[4:5], 0
	s_waitcnt vmcnt(2)
	v_lshlrev_b32_e32 v106, 16, v102
	v_and_b32_e32 v107, 0xffff0000, v102
	v_lshlrev_b32_e32 v102, 16, v103
	v_and_b32_e32 v103, 0xffff0000, v103
	v_lshlrev_b32_e32 v108, 16, v104
	v_and_b32_e32 v109, 0xffff0000, v104
	v_lshlrev_b32_e32 v104, 16, v105
	v_and_b32_e32 v105, 0xffff0000, v105
	v_pk_add_f32 v[112:113], v[96:97], v[102:103]
	v_pk_add_f32 v[102:103], v[94:95], v[106:107]
	v_pk_add_f32 v[106:107], v[92:93], v[104:105]
	v_pk_add_f32 v[104:105], v[90:91], v[108:109]
	v_cvt_pk_bf16_f32 v102, v102, v103
	v_cvt_pk_bf16_f32 v103, v112, v113
	s_nop 0
	v_cvt_pk_bf16_f32 v104, v104, v105
	v_cvt_pk_bf16_f32 v105, v106, v107
	global_load_dwordx4 v[106:109], v[110:111], off offset:256
	s_nop 0
	v_lshlrev_b32_e32 v254, 16, v102
	v_mul_f32_e32 v253, v254, v254
	v_and_b32_e32 v254, 0xffff0000, v102
	v_fmac_f32_e32 v253, v254, v254
	v_lshlrev_b32_e32 v254, 16, v103
	v_fmac_f32_e32 v253, v254, v254
	v_and_b32_e32 v254, 0xffff0000, v103
	v_fmac_f32_e32 v253, v254, v254
	v_lshlrev_b32_e32 v254, 16, v104
	v_fmac_f32_e32 v253, v254, v254
	v_and_b32_e32 v254, 0xffff0000, v104
	v_fmac_f32_e32 v253, v254, v254
	v_lshlrev_b32_e32 v254, 16, v105
	v_fmac_f32_e32 v253, v254, v254
	v_and_b32_e32 v254, 0xffff0000, v105
	v_fmac_f32_e32 v253, v254, v254
	global_store_dwordx4 v[110:111], v[102:105], off
	s_waitcnt vmcnt(1)
	s_nop 0
	v_lshlrev_b32_e32 v102, 16, v106
	v_and_b32_e32 v103, 0xffff0000, v106
	v_lshlrev_b32_e32 v104, 16, v107
	v_and_b32_e32 v105, 0xffff0000, v107
	v_lshlrev_b32_e32 v106, 16, v108
	v_and_b32_e32 v107, 0xffff0000, v108
	v_lshlrev_b32_e32 v108, 16, v109
	v_and_b32_e32 v109, 0xffff0000, v109
	v_pk_add_f32 v[104:105], v[88:89], v[104:105]
	v_pk_add_f32 v[102:103], v[86:87], v[102:103]
	v_pk_add_f32 v[108:109], v[84:85], v[108:109]
	v_pk_add_f32 v[106:107], v[82:83], v[106:107]
	v_or_b32_e32 v84, 48, v144
	v_ashrrev_i32_e32 v85, 31, v84
	v_lshlrev_b64 v[82:83], 11, v[84:85]
	v_lshl_add_u64 v[82:83], s[60:61], 0, v[82:83]
	v_lshl_add_u64 v[94:95], v[142:143], 1, v[82:83]
	global_load_dwordx4 v[86:89], v[94:95], off
	v_cvt_pk_bf16_f32 v102, v102, v103
	v_cvt_pk_bf16_f32 v103, v104, v105
	s_nop 0
	v_cvt_pk_bf16_f32 v104, v106, v107
	v_cvt_pk_bf16_f32 v105, v108, v109
	v_lshlrev_b32_e32 v254, 16, v102
	v_fmac_f32_e32 v253, v254, v254
	v_and_b32_e32 v254, 0xffff0000, v102
	v_fmac_f32_e32 v253, v254, v254
	v_lshlrev_b32_e32 v254, 16, v103
	v_fmac_f32_e32 v253, v254, v254
	v_and_b32_e32 v254, 0xffff0000, v103
	v_fmac_f32_e32 v253, v254, v254
	v_lshlrev_b32_e32 v254, 16, v104
	v_fmac_f32_e32 v253, v254, v254
	v_and_b32_e32 v254, 0xffff0000, v104
	v_fmac_f32_e32 v253, v254, v254
	v_lshlrev_b32_e32 v254, 16, v105
	v_fmac_f32_e32 v253, v254, v254
	v_and_b32_e32 v254, 0xffff0000, v105
	v_fmac_f32_e32 v253, v254, v254
	global_store_dwordx4 v[110:111], v[102:105], off offset:256
	global_store_dword v255, v253, s[100:101] offset:128

; __device__ __forceinline__ u32x4 pack8(const f32x4 a, const f32x4 b) { u32x4 w; w.x = cvt_pk_bf16(a[0], a[1]); w.y = cvt_pk_bf16(a[2], a[3]); w.z = cvt_pk_bf16(b[0], b[1]); w.w = cvt_pk_bf16(b[2], b[3]); return w; }
;     __device__ __forceinline__ void operator()(const f32x4 (&acc)[2][2][4][2], const Unit& u, int wr, int wc, int fr, int fq) const {
;     ...
;             for (int m = 0; m < 4; ++m) { const int row = row0 + ai * HALF + m * 16; bf16_t* hp = Hx + (size_t)row * 1024;
;                 if (from_f32) { const float* xin = row < 16384 ? xa + (size_t)row * 1024 : xb + (size_t)(row - 16384) * 1024;
; #pragma unroll
;                     for (int bj = 0; bj < 2; ++bj) { const int c = col0 + bj * HALF; const f32x4 r0 = *(const f32x4*)(xin + c), r1 = *(const f32x4*)(xin + c + 4);
;                         *(u32x4*)(hp + c) = pack8(r0 + acc[ai][bj][m][0], r1 + acc[ai][bj][m][1]); }
;                 } else {
; #pragma unroll
;                     for (int bj = 0; bj < 2; ++bj) { const int c = col0 + bj * HALF; const u32x4 w = *(const u32x4*)(hp + c); f32x4 r0, r1;
;                         r0[0] = __uint_as_float(w.x << 16); r0[1] = __uint_as_float(w.x & 0xffff0000u); r0[2] = __uint_as_float(w.y << 16); r0[3] = __uint_as_float(w.y & 0xffff0000u);
;                         r1[0] = __uint_as_float(w.z << 16); r1[1] = __uint_as_float(w.z & 0xffff0000u); r1[2] = __uint_as_float(w.w << 16); r1[3] = __uint_as_float(w.w & 0xffff0000u);
;                         *(u32x4*)(hp + c) = pack8(r0 + acc[ai][bj][m][0], r1 + acc[ai][bj][m][1]); }
.LBB0_97:
	s_nop 1
	v_or_b32_e32 v84, 48, v144
	v_ashrrev_i32_e32 v85, 31, v84
	v_lshlrev_b64 v[82:83], 11, v[84:85]
	v_lshl_add_u64 v[82:83], s[60:61], 0, v[82:83]
	s_and_b64 vcc, exec, s[8:9]
	s_mov_b64 s[4:5], -1
	s_cbranch_vccnz .LBB0_99
	v_lshl_add_u64 v[94:95], v[142:143], 1, v[82:83]
	s_mov_b64 s[4:5], 0
	s_waitcnt vmcnt(2)
	v_lshlrev_b32_e32 v90, 16, v86
	v_and_b32_e32 v91, 0xffff0000, v86
	v_lshlrev_b32_e32 v86, 16, v87
	v_and_b32_e32 v87, 0xffff0000, v87
	v_lshlrev_b32_e32 v92, 16, v88
	v_and_b32_e32 v93, 0xffff0000, v88
	v_lshlrev_b32_e32 v88, 16, v89
	v_and_b32_e32 v89, 0xffff0000, v89
	v_pk_add_f32 v[96:97], v[80:81], v[86:87]
	v_pk_add_f32 v[86:87], v[78:79], v[90:91]
	v_pk_add_f32 v[90:91], v[76:77], v[88:89]
	v_pk_add_f32 v[88:89], v[74:75], v[92:93]
	v_cvt_pk_bf16_f32 v86, v86, v87
	v_cvt_pk_bf16_f32 v87, v96, v97
	s_nop 0
	v_cvt_pk_bf16_f32 v88, v88, v89
	v_cvt_pk_bf16_f32 v89, v90, v91
	global_load_dwordx4 v[90:93], v[94:95], off offset:256
	s_nop 0
	v_lshlrev_b32_e32 v254, 16, v86
	v_mul_f32_e32 v253, v254, v254
	v_and_b32_e32 v254, 0xffff0000, v86
	v_fmac_f32_e32 v253, v254, v254
	v_lshlrev_b32_e32 v254, 16, v87
	v_fmac_f32_e32 v253, v254, v254
	v_and_b32_e32 v254, 0xffff0000, v87
	v_fmac_f32_e32 v253, v254, v254
	v_lshlrev_b32_e32 v254, 16, v88
	v_fmac_f32_e32 v253, v254, v254
	v_and_b32_e32 v254, 0xffff0000, v88
	v_fmac_f32_e32 v253, v254, v254
	v_lshlrev_b32_e32 v254, 16, v89
	v_fmac_f32_e32 v253, v254, v254
	v_and_b32_e32 v254, 0xffff0000, v89
	v_fmac_f32_e32 v253, v254, v254
	global_store_dwordx4 v[94:95], v[86:89], off
	s_waitcnt vmcnt(1)
	s_nop 0
	v_lshlrev_b32_e32 v86, 16, v90
	v_and_b32_e32 v87, 0xffff0000, v90
	v_lshlrev_b32_e32 v88, 16, v91
	v_and_b32_e32 v89, 0xffff0000, v91
	v_lshlrev_b32_e32 v90, 16, v92
	v_and_b32_e32 v91, 0xffff0000, v92
	v_lshlrev_b32_e32 v92, 16, v93
	v_and_b32_e32 v93, 0xffff0000, v93
	v_pk_add_f32 v[88:89], v[72:73], v[88:89]
	v_pk_add_f32 v[86:87], v[70:71], v[86:87]
	v_pk_add_f32 v[92:93], v[68:69], v[92:93]
	v_pk_add_f32 v[90:91], v[66:67], v[90:91]
	v_add_u32_e32 v68, 0x80, v144
	v_ashrrev_i32_e32 v69, 31, v68
	v_lshlrev_b64 v[66:67], 11, v[68:69]
	v_lshl_add_u64 v[66:67], s[60:61], 0, v[66:67]
	v_lshl_add_u64 v[78:79], v[142:143], 1, v[66:67]
	global_load_dwordx4 v[70:73], v[78:79], off
	v_cvt_pk_bf16_f32 v86, v86, v87
	v_cvt_pk_bf16_f32 v87, v88, v89
	s_nop 0
	v_cvt_pk_bf16_f32 v88, v90, v91
	v_cvt_pk_bf16_f32 v89, v92, v93
	v_lshlrev_b32_e32 v254, 16, v86
	v_fmac_f32_e32 v253, v254, v254
	v_and_b32_e32 v254, 0xffff0000, v86
	v_fmac_f32_e32 v253, v254, v254
	v_lshlrev_b32_e32 v254, 16, v87
	v_fmac_f32_e32 v253, v254, v254
	v_and_b32_e32 v254, 0xffff0000, v87
	v_fmac_f32_e32 v253, v254, v254
	v_lshlrev_b32_e32 v254, 16, v88
	v_fmac_f32_e32 v253, v254, v254
	v_and_b32_e32 v254, 0xffff0000, v88
	v_fmac_f32_e32 v253, v254, v254
	v_lshlrev_b32_e32 v254, 16, v89
	v_fmac_f32_e32 v253, v254, v254
	v_and_b32_e32 v254, 0xffff0000, v89
	v_fmac_f32_e32 v253, v254, v254
	global_store_dwordx4 v[94:95], v[86:89], off offset:256
	global_store_dword v255, v253, s[100:101] offset:192

; __device__ __forceinline__ u32x4 pack8(const f32x4 a, const f32x4 b) { u32x4 w; w.x = cvt_pk_bf16(a[0], a[1]); w.y = cvt_pk_bf16(a[2], a[3]); w.z = cvt_pk_bf16(b[0], b[1]); w.w = cvt_pk_bf16(b[2], b[3]); return w; }
;     __device__ __forceinline__ void operator()(const f32x4 (&acc)[2][2][4][2], const Unit& u, int wr, int wc, int fr, int fq) const {
;     ...
;             for (int m = 0; m < 4; ++m) { const int row = row0 + ai * HALF + m * 16; bf16_t* hp = Hx + (size_t)row * 1024;
;                 if (from_f32) { const float* xin = row < 16384 ? xa + (size_t)row * 1024 : xb + (size_t)(row - 16384) * 1024;
; #pragma unroll
;                     for (int bj = 0; bj < 2; ++bj) { const int c = col0 + bj * HALF; const f32x4 r0 = *(const f32x4*)(xin + c), r1 = *(const f32x4*)(xin + c + 4);
;                         *(u32x4*)(hp + c) = pack8(r0 + acc[ai][bj][m][0], r1 + acc[ai][bj][m][1]); }
;                 } else {
; #pragma unroll
;                     for (int bj = 0; bj < 2; ++bj) { const int c = col0 + bj * HALF; const u32x4 w = *(const u32x4*)(hp + c); f32x4 r0, r1;
;                         r0[0] = __uint_as_float(w.x << 16); r0[1] = __uint_as_float(w.x & 0xffff0000u); r0[2] = __uint_as_float(w.y << 16); r0[3] = __uint_as_float(w.y & 0xffff0000u);
;                         r1[0] = __uint_as_float(w.z << 16); r1[1] = __uint_as_float(w.z & 0xffff0000u); r1[2] = __uint_as_float(w.w << 16); r1[3] = __uint_as_float(w.w & 0xffff0000u);
;                         *(u32x4*)(hp + c) = pack8(r0 + acc[ai][bj][m][0], r1 + acc[ai][bj][m][1]); }
.LBB0_101:
	s_nop 1
	v_add_u32_e32 v68, 0x80, v144
	v_ashrrev_i32_e32 v69, 31, v68
	v_lshlrev_b64 v[66:67], 11, v[68:69]
	v_lshl_add_u64 v[66:67], s[60:61], 0, v[66:67]
	s_and_b64 vcc, exec, s[8:9]
	s_mov_b64 s[4:5], -1
	s_cbranch_vccnz .LBB0_103
	v_lshl_add_u64 v[78:79], v[142:143], 1, v[66:67]
	s_mov_b64 s[4:5], 0
	s_waitcnt vmcnt(2)
	v_lshlrev_b32_e32 v74, 16, v70
	v_and_b32_e32 v75, 0xffff0000, v70
	v_lshlrev_b32_e32 v70, 16, v71
	v_and_b32_e32 v71, 0xffff0000, v71
	v_lshlrev_b32_e32 v76, 16, v72
	v_and_b32_e32 v77, 0xffff0000, v72
	v_lshlrev_b32_e32 v72, 16, v73
	v_and_b32_e32 v73, 0xffff0000, v73
	v_pk_add_f32 v[80:81], v[64:65], v[70:71]
	v_pk_add_f32 v[70:71], v[62:63], v[74:75]
	v_pk_add_f32 v[74:75], v[60:61], v[72:73]
	v_pk_add_f32 v[72:73], v[58:59], v[76:77]
	v_cvt_pk_bf16_f32 v70, v70, v71
	v_cvt_pk_bf16_f32 v71, v80, v81
	s_nop 0
	v_cvt_pk_bf16_f32 v72, v72, v73
	v_cvt_pk_bf16_f32 v73, v74, v75
	global_load_dwordx4 v[74:77], v[78:79], off offset:256
	s_nop 0
	v_lshlrev_b32_e32 v254, 16, v70
	v_mul_f32_e32 v253, v254, v254
	v_and_b32_e32 v254, 0xffff0000, v70
	v_fmac_f32_e32 v253, v254, v254
	v_lshlrev_b32_e32 v254, 16, v71
	v_fmac_f32_e32 v253, v254, v254
	v_and_b32_e32 v254, 0xffff0000, v71
	v_fmac_f32_e32 v253, v254, v254
	v_lshlrev_b32_e32 v254, 16, v72
	v_fmac_f32_e32 v253, v254, v254
	v_and_b32_e32 v254, 0xffff0000, v72
	v_fmac_f32_e32 v253, v254, v254
	v_lshlrev_b32_e32 v254, 16, v73
	v_fmac_f32_e32 v253, v254, v254
	v_and_b32_e32 v254, 0xffff0000, v73
	v_fmac_f32_e32 v253, v254, v254
	global_store_dwordx4 v[78:79], v[70:73], off
	s_waitcnt vmcnt(1)
	s_nop 0
	v_lshlrev_b32_e32 v70, 16, v74
	v_and_b32_e32 v71, 0xffff0000, v74
	v_lshlrev_b32_e32 v72, 16, v75
	v_and_b32_e32 v73, 0xffff0000, v75
	v_lshlrev_b32_e32 v74, 16, v76
	v_and_b32_e32 v75, 0xffff0000, v76
	v_lshlrev_b32_e32 v76, 16, v77
	v_and_b32_e32 v77, 0xffff0000, v77
	v_pk_add_f32 v[72:73], v[56:57], v[72:73]
	v_pk_add_f32 v[70:71], v[54:55], v[70:71]
	v_pk_add_f32 v[76:77], v[52:53], v[76:77]
	v_pk_add_f32 v[74:75], v[50:51], v[74:75]
	v_add_u32_e32 v52, 0x90, v144
	v_ashrrev_i32_e32 v53, 31, v52
	v_lshlrev_b64 v[50:51], 11, v[52:53]
	v_lshl_add_u64 v[50:51], s[60:61], 0, v[50:51]
	v_lshl_add_u64 v[62:63], v[142:143], 1, v[50:51]
	global_load_dwordx4 v[54:57], v[62:63], off
	v_cvt_pk_bf16_f32 v70, v70, v71
	v_cvt_pk_bf16_f32 v71, v72, v73
	s_nop 0
	v_cvt_pk_bf16_f32 v72, v74, v75
	v_cvt_pk_bf16_f32 v73, v76, v77
	v_lshlrev_b32_e32 v254, 16, v70
	v_fmac_f32_e32 v253, v254, v254
	v_and_b32_e32 v254, 0xffff0000, v70
	v_fmac_f32_e32 v253, v254, v254
	v_lshlrev_b32_e32 v254, 16, v71
	v_fmac_f32_e32 v253, v254, v254
	v_and_b32_e32 v254, 0xffff0000, v71
	v_fmac_f32_e32 v253, v254, v254
	v_lshlrev_b32_e32 v254, 16, v72
	v_fmac_f32_e32 v253, v254, v254
	v_and_b32_e32 v254, 0xffff0000, v72
	v_fmac_f32_e32 v253, v254, v254
	v_lshlrev_b32_e32 v254, 16, v73
	v_fmac_f32_e32 v253, v254, v254
	v_and_b32_e32 v254, 0xffff0000, v73
	v_fmac_f32_e32 v253, v254, v254
	global_store_dwordx4 v[78:79], v[70:73], off offset:256
	global_store_dword v255, v253, s[100:101] offset:512

; __device__ __forceinline__ u32x4 pack8(const f32x4 a, const f32x4 b) { u32x4 w; w.x = cvt_pk_bf16(a[0], a[1]); w.y = cvt_pk_bf16(a[2], a[3]); w.z = cvt_pk_bf16(b[0], b[1]); w.w = cvt_pk_bf16(b[2], b[3]); return w; }
;     __device__ __forceinline__ void operator()(const f32x4 (&acc)[2][2][4][2], const Unit& u, int wr, int wc, int fr, int fq) const {
;     ...
;             for (int m = 0; m < 4; ++m) { const int row = row0 + ai * HALF + m * 16; bf16_t* hp = Hx + (size_t)row * 1024;
;                 if (from_f32) { const float* xin = row < 16384 ? xa + (size_t)row * 1024 : xb + (size_t)(row - 16384) * 1024;
; #pragma unroll
;                     for (int bj = 0; bj < 2; ++bj) { const int c = col0 + bj * HALF; const f32x4 r0 = *(const f32x4*)(xin + c), r1 = *(const f32x4*)(xin + c + 4);
;                         *(u32x4*)(hp + c) = pack8(r0 + acc[ai][bj][m][0], r1 + acc[ai][bj][m][1]); }
;                 } else {
; #pragma unroll
;                     for (int bj = 0; bj < 2; ++bj) { const int c = col0 + bj * HALF; const u32x4 w = *(const u32x4*)(hp + c); f32x4 r0, r1;
;                         r0[0] = __uint_as_float(w.x << 16); r0[1] = __uint_as_float(w.x & 0xffff0000u); r0[2] = __uint_as_float(w.y << 16); r0[3] = __uint_as_float(w.y & 0xffff0000u);
;                         r1[0] = __uint_as_float(w.z << 16); r1[1] = __uint_as_float(w.z & 0xffff0000u); r1[2] = __uint_as_float(w.w << 16); r1[3] = __uint_as_float(w.w & 0xffff0000u);
;                         *(u32x4*)(hp + c) = pack8(r0 + acc[ai][bj][m][0], r1 + acc[ai][bj][m][1]); }
.LBB0_105:
	s_nop 1
	v_add_u32_e32 v52, 0x90, v144
	v_ashrrev_i32_e32 v53, 31, v52
	v_lshlrev_b64 v[50:51], 11, v[52:53]
	v_lshl_add_u64 v[50:51], s[60:61], 0, v[50:51]
	s_and_b64 vcc, exec, s[8:9]
	s_mov_b64 s[4:5], -1
	s_cbranch_vccnz .LBB0_107
	v_lshl_add_u64 v[62:63], v[142:143], 1, v[50:51]
	s_mov_b64 s[4:5], 0
	s_waitcnt vmcnt(2)
	v_lshlrev_b32_e32 v58, 16, v54
	v_and_b32_e32 v59, 0xffff0000, v54
	v_lshlrev_b32_e32 v54, 16, v55
	v_and_b32_e32 v55, 0xffff0000, v55
	v_lshlrev_b32_e32 v60, 16, v56
	v_and_b32_e32 v61, 0xffff0000, v56
	v_lshlrev_b32_e32 v56, 16, v57
	v_and_b32_e32 v57, 0xffff0000, v57
	v_pk_add_f32 v[64:65], v[48:49], v[54:55]
	v_pk_add_f32 v[54:55], v[46:47], v[58:59]
	v_pk_add_f32 v[58:59], v[44:45], v[56:57]
	v_pk_add_f32 v[56:57], v[42:43], v[60:61]
	v_cvt_pk_bf16_f32 v54, v54, v55
	v_cvt_pk_bf16_f32 v55, v64, v65
	s_nop 0
	v_cvt_pk_bf16_f32 v56, v56, v57
	v_cvt_pk_bf16_f32 v57, v58, v59
	global_load_dwordx4 v[58:61], v[62:63], off offset:256
	s_nop 0
	v_lshlrev_b32_e32 v254, 16, v54
	v_mul_f32_e32 v253, v254, v254
	v_and_b32_e32 v254, 0xffff0000, v54
	v_fmac_f32_e32 v253, v254, v254
	v_lshlrev_b32_e32 v254, 16, v55
	v_fmac_f32_e32 v253, v254, v254
	v_and_b32_e32 v254, 0xffff0000, v55
	v_fmac_f32_e32 v253, v254, v254
	v_lshlrev_b32_e32 v254, 16, v56
	v_fmac_f32_e32 v253, v254, v254
	v_and_b32_e32 v254, 0xffff0000, v56
	v_fmac_f32_e32 v253, v254, v254
	v_lshlrev_b32_e32 v254, 16, v57
	v_fmac_f32_e32 v253, v254, v254
	v_and_b32_e32 v254, 0xffff0000, v57
	v_fmac_f32_e32 v253, v254, v254
	global_store_dwordx4 v[62:63], v[54:57], off
	s_waitcnt vmcnt(1)
	s_nop 0
	v_lshlrev_b32_e32 v54, 16, v58
	v_and_b32_e32 v55, 0xffff0000, v58
	v_lshlrev_b32_e32 v56, 16, v59
	v_and_b32_e32 v57, 0xffff0000, v59
	v_lshlrev_b32_e32 v58, 16, v60
	v_and_b32_e32 v59, 0xffff0000, v60
	v_lshlrev_b32_e32 v60, 16, v61
	v_and_b32_e32 v61, 0xffff0000, v61
	v_pk_add_f32 v[56:57], v[40:41], v[56:57]
	v_pk_add_f32 v[54:55], v[38:39], v[54:55]
	v_pk_add_f32 v[60:61], v[36:37], v[60:61]
	v_pk_add_f32 v[58:59], v[34:35], v[58:59]
	v_add_u32_e32 v36, 0xa0, v144
	v_ashrrev_i32_e32 v37, 31, v36
	v_lshlrev_b64 v[34:35], 11, v[36:37]
	v_lshl_add_u64 v[34:35], s[60:61], 0, v[34:35]
	v_lshl_add_u64 v[46:47], v[142:143], 1, v[34:35]
	global_load_dwordx4 v[38:41], v[46:47], off
	v_cvt_pk_bf16_f32 v54, v54, v55
	v_cvt_pk_bf16_f32 v55, v56, v57
	s_nop 0
	v_cvt_pk_bf16_f32 v56, v58, v59
	v_cvt_pk_bf16_f32 v57, v60, v61
	v_lshlrev_b32_e32 v254, 16, v54
	v_fmac_f32_e32 v253, v254, v254
	v_and_b32_e32 v254, 0xffff0000, v54
	v_fmac_f32_e32 v253, v254, v254
	v_lshlrev_b32_e32 v254, 16, v55
	v_fmac_f32_e32 v253, v254, v254
	v_and_b32_e32 v254, 0xffff0000, v55
	v_fmac_f32_e32 v253, v254, v254
	v_lshlrev_b32_e32 v254, 16, v56
	v_fmac_f32_e32 v253, v254, v254
	v_and_b32_e32 v254, 0xffff0000, v56
	v_fmac_f32_e32 v253, v254, v254
	v_lshlrev_b32_e32 v254, 16, v57
	v_fmac_f32_e32 v253, v254, v254
	v_and_b32_e32 v254, 0xffff0000, v57
	v_fmac_f32_e32 v253, v254, v254
	global_store_dwordx4 v[62:63], v[54:57], off offset:256
	global_store_dword v255, v253, s[100:101] offset:576

; __device__ __forceinline__ u32x4 pack8(const f32x4 a, const f32x4 b) { u32x4 w; w.x = cvt_pk_bf16(a[0], a[1]); w.y = cvt_pk_bf16(a[2], a[3]); w.z = cvt_pk_bf16(b[0], b[1]); w.w = cvt_pk_bf16(b[2], b[3]); return w; }
;     __device__ __forceinline__ void operator()(const f32x4 (&acc)[2][2][4][2], const Unit& u, int wr, int wc, int fr, int fq) const {
;     ...
;             for (int m = 0; m < 4; ++m) { const int row = row0 + ai * HALF + m * 16; bf16_t* hp = Hx + (size_t)row * 1024;
;                 if (from_f32) { const float* xin = row < 16384 ? xa + (size_t)row * 1024 : xb + (size_t)(row - 16384) * 1024;
; #pragma unroll
;                     for (int bj = 0; bj < 2; ++bj) { const int c = col0 + bj * HALF; const f32x4 r0 = *(const f32x4*)(xin + c), r1 = *(const f32x4*)(xin + c + 4);
;                         *(u32x4*)(hp + c) = pack8(r0 + acc[ai][bj][m][0], r1 + acc[ai][bj][m][1]); }
;                 } else {
; #pragma unroll
;                     for (int bj = 0; bj < 2; ++bj) { const int c = col0 + bj * HALF; const u32x4 w = *(const u32x4*)(hp + c); f32x4 r0, r1;
;                         r0[0] = __uint_as_float(w.x << 16); r0[1] = __uint_as_float(w.x & 0xffff0000u); r0[2] = __uint_as_float(w.y << 16); r0[3] = __uint_as_float(w.y & 0xffff0000u);
;                         r1[0] = __uint_as_float(w.z << 16); r1[1] = __uint_as_float(w.z & 0xffff0000u); r1[2] = __uint_as_float(w.w << 16); r1[3] = __uint_as_float(w.w & 0xffff0000u);
;                         *(u32x4*)(hp + c) = pack8(r0 + acc[ai][bj][m][0], r1 + acc[ai][bj][m][1]); }
.LBB0_109:
	s_nop 1
	v_add_u32_e32 v36, 0xa0, v144
	v_ashrrev_i32_e32 v37, 31, v36
	v_lshlrev_b64 v[34:35], 11, v[36:37]
	v_lshl_add_u64 v[34:35], s[60:61], 0, v[34:35]
	s_and_b64 vcc, exec, s[8:9]
	s_mov_b64 s[4:5], -1
	s_cbranch_vccnz .LBB0_111
	v_lshl_add_u64 v[46:47], v[142:143], 1, v[34:35]
	s_mov_b64 s[4:5], 0
	s_waitcnt vmcnt(2)
	v_lshlrev_b32_e32 v42, 16, v38
	v_and_b32_e32 v43, 0xffff0000, v38
	v_lshlrev_b32_e32 v38, 16, v39
	v_and_b32_e32 v39, 0xffff0000, v39
	v_lshlrev_b32_e32 v44, 16, v40
	v_and_b32_e32 v45, 0xffff0000, v40
	v_lshlrev_b32_e32 v40, 16, v41
	v_and_b32_e32 v41, 0xffff0000, v41
	v_pk_add_f32 v[48:49], v[32:33], v[38:39]
	v_pk_add_f32 v[38:39], v[30:31], v[42:43]
	v_pk_add_f32 v[42:43], v[28:29], v[40:41]
	v_pk_add_f32 v[40:41], v[26:27], v[44:45]
	v_cvt_pk_bf16_f32 v38, v38, v39
	v_cvt_pk_bf16_f32 v39, v48, v49
	s_nop 0
	v_cvt_pk_bf16_f32 v40, v40, v41
	v_cvt_pk_bf16_f32 v41, v42, v43
	global_load_dwordx4 v[42:45], v[46:47], off offset:256
	s_nop 0
	v_lshlrev_b32_e32 v254, 16, v38
	v_mul_f32_e32 v253, v254, v254
	v_and_b32_e32 v254, 0xffff0000, v38
	v_fmac_f32_e32 v253, v254, v254
	v_lshlrev_b32_e32 v254, 16, v39
	v_fmac_f32_e32 v253, v254, v254
	v_and_b32_e32 v254, 0xffff0000, v39
	v_fmac_f32_e32 v253, v254, v254
	v_lshlrev_b32_e32 v254, 16, v40
	v_fmac_f32_e32 v253, v254, v254
	v_and_b32_e32 v254, 0xffff0000, v40
	v_fmac_f32_e32 v253, v254, v254
	v_lshlrev_b32_e32 v254, 16, v41
	v_fmac_f32_e32 v253, v254, v254
	v_and_b32_e32 v254, 0xffff0000, v41
	v_fmac_f32_e32 v253, v254, v254
	global_store_dwordx4 v[46:47], v[38:41], off
	s_waitcnt vmcnt(1)
	s_nop 0
	v_lshlrev_b32_e32 v38, 16, v42
	v_and_b32_e32 v39, 0xffff0000, v42
	v_lshlrev_b32_e32 v40, 16, v43
	v_and_b32_e32 v41, 0xffff0000, v43
	v_lshlrev_b32_e32 v42, 16, v44
	v_and_b32_e32 v43, 0xffff0000, v44
	v_lshlrev_b32_e32 v44, 16, v45
	v_and_b32_e32 v45, 0xffff0000, v45
	v_pk_add_f32 v[40:41], v[24:25], v[40:41]
	v_pk_add_f32 v[38:39], v[22:23], v[38:39]
	v_pk_add_f32 v[44:45], v[20:21], v[44:45]
	v_pk_add_f32 v[42:43], v[18:19], v[42:43]
	v_add_u32_e32 v20, 0xb0, v144
	v_ashrrev_i32_e32 v21, 31, v20
	v_lshlrev_b64 v[18:19], 11, v[20:21]
	v_lshl_add_u64 v[18:19], s[60:61], 0, v[18:19]
	v_lshl_add_u64 v[30:31], v[142:143], 1, v[18:19]
	global_load_dwordx4 v[22:25], v[30:31], off
	v_cvt_pk_bf16_f32 v38, v38, v39
	v_cvt_pk_bf16_f32 v39, v40, v41
	s_nop 0
	v_cvt_pk_bf16_f32 v40, v42, v43
	v_cvt_pk_bf16_f32 v41, v44, v45
	v_lshlrev_b32_e32 v254, 16, v38
	v_fmac_f32_e32 v253, v254, v254
	v_and_b32_e32 v254, 0xffff0000, v38
	v_fmac_f32_e32 v253, v254, v254
	v_lshlrev_b32_e32 v254, 16, v39
	v_fmac_f32_e32 v253, v254, v254
	v_and_b32_e32 v254, 0xffff0000, v39
	v_fmac_f32_e32 v253, v254, v254
	v_lshlrev_b32_e32 v254, 16, v40
	v_fmac_f32_e32 v253, v254, v254
	v_and_b32_e32 v254, 0xffff0000, v40
	v_fmac_f32_e32 v253, v254, v254
	v_lshlrev_b32_e32 v254, 16, v41
	v_fmac_f32_e32 v253, v254, v254
	v_and_b32_e32 v254, 0xffff0000, v41
	v_fmac_f32_e32 v253, v254, v254
	global_store_dwordx4 v[46:47], v[38:41], off offset:256
	global_store_dword v255, v253, s[100:101] offset:640

; __device__ __forceinline__ u32x4 pack8(const f32x4 a, const f32x4 b) { u32x4 w; w.x = cvt_pk_bf16(a[0], a[1]); w.y = cvt_pk_bf16(a[2], a[3]); w.z = cvt_pk_bf16(b[0], b[1]); w.w = cvt_pk_bf16(b[2], b[3]); return w; }
;     __device__ __forceinline__ void operator()(const f32x4 (&acc)[2][2][4][2], const Unit& u, int wr, int wc, int fr, int fq) const {
;     ...
;             for (int m = 0; m < 4; ++m) { const int row = row0 + ai * HALF + m * 16; bf16_t* hp = Hx + (size_t)row * 1024;
;                 if (from_f32) { const float* xin = row < 16384 ? xa + (size_t)row * 1024 : xb + (size_t)(row - 16384) * 1024;
; #pragma unroll
;                     for (int bj = 0; bj < 2; ++bj) { const int c = col0 + bj * HALF; const f32x4 r0 = *(const f32x4*)(xin + c), r1 = *(const f32x4*)(xin + c + 4);
;                         *(u32x4*)(hp + c) = pack8(r0 + acc[ai][bj][m][0], r1 + acc[ai][bj][m][1]); }
;                 } else {
; #pragma unroll
;                     for (int bj = 0; bj < 2; ++bj) { const int c = col0 + bj * HALF; const u32x4 w = *(const u32x4*)(hp + c); f32x4 r0, r1;
;                         r0[0] = __uint_as_float(w.x << 16); r0[1] = __uint_as_float(w.x & 0xffff0000u); r0[2] = __uint_as_float(w.y << 16); r0[3] = __uint_as_float(w.y & 0xffff0000u);
;                         r1[0] = __uint_as_float(w.z << 16); r1[1] = __uint_as_float(w.z & 0xffff0000u); r1[2] = __uint_as_float(w.w << 16); r1[3] = __uint_as_float(w.w & 0xffff0000u);
;                         *(u32x4*)(hp + c) = pack8(r0 + acc[ai][bj][m][0], r1 + acc[ai][bj][m][1]); }
.LBB0_113:
	s_nop 1
	v_add_u32_e32 v20, 0xb0, v144
	v_ashrrev_i32_e32 v21, 31, v20
	v_lshlrev_b64 v[18:19], 11, v[20:21]
	v_lshl_add_u64 v[18:19], s[60:61], 0, v[18:19]
	s_and_b64 vcc, exec, s[8:9]
	s_mov_b64 s[4:5], -1
	s_cbranch_vccnz .LBB0_115
	v_lshl_add_u64 v[30:31], v[142:143], 1, v[18:19]
	s_mov_b64 s[4:5], 0
	s_waitcnt vmcnt(2)
	v_lshlrev_b32_e32 v26, 16, v22
	v_and_b32_e32 v27, 0xffff0000, v22
	v_lshlrev_b32_e32 v22, 16, v23
	v_and_b32_e32 v23, 0xffff0000, v23
	v_lshlrev_b32_e32 v28, 16, v24
	v_and_b32_e32 v29, 0xffff0000, v24
	v_lshlrev_b32_e32 v24, 16, v25
	v_and_b32_e32 v25, 0xffff0000, v25
	v_pk_add_f32 v[32:33], v[16:17], v[22:23]
	v_pk_add_f32 v[22:23], v[14:15], v[26:27]
	v_pk_add_f32 v[26:27], v[12:13], v[24:25]
	v_pk_add_f32 v[24:25], v[10:11], v[28:29]
	v_cvt_pk_bf16_f32 v22, v22, v23
	v_cvt_pk_bf16_f32 v23, v32, v33
	s_nop 0
	v_cvt_pk_bf16_f32 v24, v24, v25
	v_cvt_pk_bf16_f32 v25, v26, v27
	global_load_dwordx4 v[26:29], v[30:31], off offset:256
	s_nop 0
	v_lshlrev_b32_e32 v254, 16, v22
	v_mul_f32_e32 v253, v254, v254
	v_and_b32_e32 v254, 0xffff0000, v22
	v_fmac_f32_e32 v253, v254, v254
	v_lshlrev_b32_e32 v254, 16, v23
	v_fmac_f32_e32 v253, v254, v254
	v_and_b32_e32 v254, 0xffff0000, v23
	v_fmac_f32_e32 v253, v254, v254
	v_lshlrev_b32_e32 v254, 16, v24
	v_fmac_f32_e32 v253, v254, v254
	v_and_b32_e32 v254, 0xffff0000, v24
	v_fmac_f32_e32 v253, v254, v254
	v_lshlrev_b32_e32 v254, 16, v25
	v_fmac_f32_e32 v253, v254, v254
	v_and_b32_e32 v254, 0xffff0000, v25
	v_fmac_f32_e32 v253, v254, v254
	global_store_dwordx4 v[30:31], v[22:25], off
	s_waitcnt vmcnt(1)
	s_nop 0
	v_lshlrev_b32_e32 v22, 16, v26
	v_and_b32_e32 v23, 0xffff0000, v26
	v_lshlrev_b32_e32 v24, 16, v27
	v_and_b32_e32 v25, 0xffff0000, v27
	v_lshlrev_b32_e32 v26, 16, v28
	v_and_b32_e32 v27, 0xffff0000, v28
	v_lshlrev_b32_e32 v28, 16, v29
	v_and_b32_e32 v29, 0xffff0000, v29
	v_pk_add_f32 v[24:25], v[8:9], v[24:25]
	v_pk_add_f32 v[22:23], v[6:7], v[22:23]
	v_pk_add_f32 v[28:29], v[4:5], v[28:29]
	v_pk_add_f32 v[26:27], v[2:3], v[26:27]
	v_cvt_pk_bf16_f32 v22, v22, v23
	v_cvt_pk_bf16_f32 v23, v24, v25
	s_nop 0
	v_cvt_pk_bf16_f32 v24, v26, v27
	v_cvt_pk_bf16_f32 v25, v28, v29
	v_lshlrev_b32_e32 v254, 16, v22
	v_fmac_f32_e32 v253, v254, v254
	v_and_b32_e32 v254, 0xffff0000, v22
	v_fmac_f32_e32 v253, v254, v254
	v_lshlrev_b32_e32 v254, 16, v23
	v_fmac_f32_e32 v253, v254, v254
	v_and_b32_e32 v254, 0xffff0000, v23
	v_fmac_f32_e32 v253, v254, v254
	v_lshlrev_b32_e32 v254, 16, v24
	v_fmac_f32_e32 v253, v254, v254
	v_and_b32_e32 v254, 0xffff0000, v24
	v_fmac_f32_e32 v253, v254, v254
	v_lshlrev_b32_e32 v254, 16, v25
	v_fmac_f32_e32 v253, v254, v254
	v_and_b32_e32 v254, 0xffff0000, v25
	v_fmac_f32_e32 v253, v254, v254
	global_store_dwordx4 v[30:31], v[22:25], off offset:256
	global_store_dword v255, v253, s[100:101] offset:704
